# HGRN chunk-state scan: all 64 per-chunk state and decay loads issued in two bulk batches with one wait each, FMA chain and stores without per-step drain
# speedup vs baseline: 1.0094x; 1.0082x over previous
; __device__ __forceinline__ int opaque_tid() { int t = threadIdx.x; asm volatile("" : "+v"(t)); return t; }
; DI void hgrn_h2(const Params& p, int item) {
;   const int bh = item >> 4, idx = (item & 15) * 256 + (opaque_tid() & 255), d = idx >> 6;
;   float S = 0.f;
;   float* ub = p.U + (size_t)bh * 64 * 4096 + idx;
;   const float* gb = p.G + (size_t)bh * 64 * 64 + d;
; #pragma unroll 8
;   for (int c = 0; c < 64; ++c) { const float u = ub[(size_t)c * 4096]; const float g = gb[c * 64]; ub[(size_t)c * 4096] = S; S = g * S + u; }
; }
.LBB0_664:
	s_mov_b64 s[6:7], 0x4000
	s_mov_b64 s[2:3], 0x1000
	v_lshl_add_u64 v[6:7], v[2:3], 0, 0
	global_load_dword v60, v[6:7], off
	v_lshl_add_u64 v[8:9], v[4:5], 0, 0
	global_load_dword v124, v[8:9], off offset:-1792
	v_lshl_add_u64 v[6:7], v[6:7], 0, s[6:7]
	global_load_dword v61, v[6:7], off
	global_load_dword v125, v[8:9], off offset:-1536
	v_lshl_add_u64 v[6:7], v[6:7], 0, s[6:7]
	global_load_dword v62, v[6:7], off
	global_load_dword v126, v[8:9], off offset:-1280
	v_lshl_add_u64 v[6:7], v[6:7], 0, s[6:7]
	global_load_dword v63, v[6:7], off
	global_load_dword v127, v[8:9], off offset:-1024
	v_lshl_add_u64 v[6:7], v[6:7], 0, s[6:7]
	global_load_dword v64, v[6:7], off
	global_load_dword v128, v[8:9], off offset:-768
	v_lshl_add_u64 v[6:7], v[6:7], 0, s[6:7]
	global_load_dword v65, v[6:7], off
	global_load_dword v129, v[8:9], off offset:-512
	v_lshl_add_u64 v[6:7], v[6:7], 0, s[6:7]
	global_load_dword v66, v[6:7], off
	global_load_dword v130, v[8:9], off offset:-256
	v_lshl_add_u64 v[6:7], v[6:7], 0, s[6:7]
	global_load_dword v67, v[6:7], off
	global_load_dword v131, v[8:9], off
	v_lshl_add_u64 v[6:7], v[6:7], 0, s[6:7]
	global_load_dword v68, v[6:7], off
	global_load_dword v132, v[8:9], off offset:256
	v_lshl_add_u64 v[6:7], v[6:7], 0, s[6:7]
	global_load_dword v69, v[6:7], off
	global_load_dword v133, v[8:9], off offset:512
	v_lshl_add_u64 v[6:7], v[6:7], 0, s[6:7]
	global_load_dword v70, v[6:7], off
	global_load_dword v134, v[8:9], off offset:768
	v_lshl_add_u64 v[6:7], v[6:7], 0, s[6:7]
	global_load_dword v71, v[6:7], off
	global_load_dword v135, v[8:9], off offset:1024
	v_lshl_add_u64 v[6:7], v[6:7], 0, s[6:7]
	global_load_dword v72, v[6:7], off
	global_load_dword v136, v[8:9], off offset:1280
	v_lshl_add_u64 v[6:7], v[6:7], 0, s[6:7]
	global_load_dword v73, v[6:7], off
	global_load_dword v137, v[8:9], off offset:1536
	v_lshl_add_u64 v[6:7], v[6:7], 0, s[6:7]
	global_load_dword v74, v[6:7], off
	global_load_dword v138, v[8:9], off offset:1792
	v_lshl_add_u64 v[6:7], v[6:7], 0, s[6:7]
	global_load_dword v75, v[6:7], off
	global_load_dword v139, v[8:9], off offset:2048
	v_lshl_add_u64 v[6:7], v[6:7], 0, s[6:7]
	global_load_dword v76, v[6:7], off
	v_lshl_add_u64 v[8:9], v[8:9], 0, s[2:3]
	global_load_dword v140, v[8:9], off offset:-1792
	v_lshl_add_u64 v[6:7], v[6:7], 0, s[6:7]
	global_load_dword v77, v[6:7], off
	global_load_dword v141, v[8:9], off offset:-1536
	v_lshl_add_u64 v[6:7], v[6:7], 0, s[6:7]
	global_load_dword v78, v[6:7], off
	global_load_dword v142, v[8:9], off offset:-1280
	v_lshl_add_u64 v[6:7], v[6:7], 0, s[6:7]
	global_load_dword v79, v[6:7], off
	global_load_dword v143, v[8:9], off offset:-1024
	v_lshl_add_u64 v[6:7], v[6:7], 0, s[6:7]
	global_load_dword v80, v[6:7], off
	global_load_dword v144, v[8:9], off offset:-768
	v_lshl_add_u64 v[6:7], v[6:7], 0, s[6:7]
	global_load_dword v81, v[6:7], off
	global_load_dword v145, v[8:9], off offset:-512
	v_lshl_add_u64 v[6:7], v[6:7], 0, s[6:7]
	global_load_dword v82, v[6:7], off
	global_load_dword v146, v[8:9], off offset:-256
	v_lshl_add_u64 v[6:7], v[6:7], 0, s[6:7]
	global_load_dword v83, v[6:7], off
	global_load_dword v147, v[8:9], off
	v_lshl_add_u64 v[6:7], v[6:7], 0, s[6:7]
	global_load_dword v84, v[6:7], off
	global_load_dword v148, v[8:9], off offset:256
	v_lshl_add_u64 v[6:7], v[6:7], 0, s[6:7]
	global_load_dword v85, v[6:7], off
	global_load_dword v149, v[8:9], off offset:512
	v_lshl_add_u64 v[6:7], v[6:7], 0, s[6:7]
	global_load_dword v86, v[6:7], off
	global_load_dword v150, v[8:9], off offset:768
	v_lshl_add_u64 v[6:7], v[6:7], 0, s[6:7]
	global_load_dword v87, v[6:7], off
	global_load_dword v151, v[8:9], off offset:1024
	v_lshl_add_u64 v[6:7], v[6:7], 0, s[6:7]
	global_load_dword v88, v[6:7], off
	global_load_dword v152, v[8:9], off offset:1280
	v_lshl_add_u64 v[6:7], v[6:7], 0, s[6:7]
	global_load_dword v89, v[6:7], off
	global_load_dword v153, v[8:9], off offset:1536
	v_lshl_add_u64 v[6:7], v[6:7], 0, s[6:7]
	global_load_dword v90, v[6:7], off
	global_load_dword v154, v[8:9], off offset:1792
	v_lshl_add_u64 v[6:7], v[6:7], 0, s[6:7]
	global_load_dword v91, v[6:7], off
	global_load_dword v155, v[8:9], off offset:2048
	s_waitcnt vmcnt(0)
	v_lshl_add_u64 v[6:7], v[6:7], 0, s[6:7]
	global_load_dword v92, v[6:7], off
	v_lshl_add_u64 v[8:9], v[8:9], 0, s[2:3]
	global_load_dword v156, v[8:9], off offset:-1792
	v_lshl_add_u64 v[6:7], v[6:7], 0, s[6:7]
	global_load_dword v93, v[6:7], off
	global_load_dword v157, v[8:9], off offset:-1536
	v_lshl_add_u64 v[6:7], v[6:7], 0, s[6:7]
	global_load_dword v94, v[6:7], off
	global_load_dword v158, v[8:9], off offset:-1280
	v_lshl_add_u64 v[6:7], v[6:7], 0, s[6:7]
	global_load_dword v95, v[6:7], off
	global_load_dword v159, v[8:9], off offset:-1024
	v_lshl_add_u64 v[6:7], v[6:7], 0, s[6:7]
	global_load_dword v96, v[6:7], off
	global_load_dword v160, v[8:9], off offset:-768
	v_lshl_add_u64 v[6:7], v[6:7], 0, s[6:7]
	global_load_dword v97, v[6:7], off
	global_load_dword v161, v[8:9], off offset:-512
	v_lshl_add_u64 v[6:7], v[6:7], 0, s[6:7]
	global_load_dword v98, v[6:7], off
	global_load_dword v162, v[8:9], off offset:-256
	v_lshl_add_u64 v[6:7], v[6:7], 0, s[6:7]
	global_load_dword v99, v[6:7], off
	global_load_dword v163, v[8:9], off
	v_lshl_add_u64 v[6:7], v[6:7], 0, s[6:7]
	global_load_dword v100, v[6:7], off
	global_load_dword v164, v[8:9], off offset:256
	v_lshl_add_u64 v[6:7], v[6:7], 0, s[6:7]
	global_load_dword v101, v[6:7], off
	global_load_dword v165, v[8:9], off offset:512
	v_lshl_add_u64 v[6:7], v[6:7], 0, s[6:7]
	global_load_dword v102, v[6:7], off
	global_load_dword v166, v[8:9], off offset:768
; __device__ __forceinline__ int opaque_tid() { int t = threadIdx.x; asm volatile("" : "+v"(t)); return t; }
; DI void hgrn_h2(const Params& p, int item) {
;   const int bh = item >> 4, idx = (item & 15) * 256 + (opaque_tid() & 255), d = idx >> 6;
;   float S = 0.f;
;   float* ub = p.U + (size_t)bh * 64 * 4096 + idx;
;   const float* gb = p.G + (size_t)bh * 64 * 64 + d;
; #pragma unroll 8
;   for (int c = 0; c < 64; ++c) { const float u = ub[(size_t)c * 4096]; const float g = gb[c * 64]; ub[(size_t)c * 4096] = S; S = g * S + u; }
; }
	v_lshl_add_u64 v[6:7], v[6:7], 0, s[6:7]
	global_load_dword v103, v[6:7], off
	global_load_dword v167, v[8:9], off offset:1024
	v_lshl_add_u64 v[6:7], v[6:7], 0, s[6:7]
	global_load_dword v104, v[6:7], off
	global_load_dword v168, v[8:9], off offset:1280
	v_lshl_add_u64 v[6:7], v[6:7], 0, s[6:7]
	global_load_dword v105, v[6:7], off
	global_load_dword v169, v[8:9], off offset:1536
	v_lshl_add_u64 v[6:7], v[6:7], 0, s[6:7]
	global_load_dword v106, v[6:7], off
	global_load_dword v170, v[8:9], off offset:1792
	v_lshl_add_u64 v[6:7], v[6:7], 0, s[6:7]
	global_load_dword v107, v[6:7], off
	global_load_dword v171, v[8:9], off offset:2048
	v_lshl_add_u64 v[6:7], v[6:7], 0, s[6:7]
	global_load_dword v108, v[6:7], off
	v_lshl_add_u64 v[8:9], v[8:9], 0, s[2:3]
	global_load_dword v172, v[8:9], off offset:-1792
	v_lshl_add_u64 v[6:7], v[6:7], 0, s[6:7]
	global_load_dword v109, v[6:7], off
	global_load_dword v173, v[8:9], off offset:-1536
	v_lshl_add_u64 v[6:7], v[6:7], 0, s[6:7]
	global_load_dword v110, v[6:7], off
	global_load_dword v174, v[8:9], off offset:-1280
	v_lshl_add_u64 v[6:7], v[6:7], 0, s[6:7]
	global_load_dword v111, v[6:7], off
	global_load_dword v175, v[8:9], off offset:-1024
	v_lshl_add_u64 v[6:7], v[6:7], 0, s[6:7]
	global_load_dword v112, v[6:7], off
	global_load_dword v176, v[8:9], off offset:-768
	v_lshl_add_u64 v[6:7], v[6:7], 0, s[6:7]
	global_load_dword v113, v[6:7], off
	global_load_dword v177, v[8:9], off offset:-512
	v_lshl_add_u64 v[6:7], v[6:7], 0, s[6:7]
	global_load_dword v114, v[6:7], off
	global_load_dword v178, v[8:9], off offset:-256
	v_lshl_add_u64 v[6:7], v[6:7], 0, s[6:7]
	global_load_dword v115, v[6:7], off
	global_load_dword v179, v[8:9], off
	v_lshl_add_u64 v[6:7], v[6:7], 0, s[6:7]
	global_load_dword v116, v[6:7], off
	global_load_dword v180, v[8:9], off offset:256
	v_lshl_add_u64 v[6:7], v[6:7], 0, s[6:7]
	global_load_dword v117, v[6:7], off
	global_load_dword v181, v[8:9], off offset:512
	v_lshl_add_u64 v[6:7], v[6:7], 0, s[6:7]
	global_load_dword v118, v[6:7], off
	global_load_dword v182, v[8:9], off offset:768
	v_lshl_add_u64 v[6:7], v[6:7], 0, s[6:7]
	global_load_dword v119, v[6:7], off
	global_load_dword v183, v[8:9], off offset:1024
	v_lshl_add_u64 v[6:7], v[6:7], 0, s[6:7]
	global_load_dword v120, v[6:7], off
	global_load_dword v184, v[8:9], off offset:1280
	v_lshl_add_u64 v[6:7], v[6:7], 0, s[6:7]
	global_load_dword v121, v[6:7], off
	global_load_dword v185, v[8:9], off offset:1536
	v_lshl_add_u64 v[6:7], v[6:7], 0, s[6:7]
	global_load_dword v122, v[6:7], off
	global_load_dword v186, v[8:9], off offset:1792
	v_lshl_add_u64 v[6:7], v[6:7], 0, s[6:7]
	global_load_dword v123, v[6:7], off
	global_load_dword v187, v[8:9], off offset:2048
	v_lshl_add_u64 v[10:11], v[2:3], 0, 0
	global_store_dword v[10:11], v0, off
	v_fmac_f32_e32 v60, v0, v124
	v_lshl_add_u64 v[10:11], v[10:11], 0, s[6:7]
	global_store_dword v[10:11], v60, off
	v_fmac_f32_e32 v61, v60, v125
	v_lshl_add_u64 v[10:11], v[10:11], 0, s[6:7]
	global_store_dword v[10:11], v61, off
	v_fmac_f32_e32 v62, v61, v126
	v_lshl_add_u64 v[10:11], v[10:11], 0, s[6:7]
	global_store_dword v[10:11], v62, off
	v_fmac_f32_e32 v63, v62, v127
	v_lshl_add_u64 v[10:11], v[10:11], 0, s[6:7]
	global_store_dword v[10:11], v63, off
	v_fmac_f32_e32 v64, v63, v128
	v_lshl_add_u64 v[10:11], v[10:11], 0, s[6:7]
	global_store_dword v[10:11], v64, off
	v_fmac_f32_e32 v65, v64, v129
	v_lshl_add_u64 v[10:11], v[10:11], 0, s[6:7]
	global_store_dword v[10:11], v65, off
	v_fmac_f32_e32 v66, v65, v130
	v_lshl_add_u64 v[10:11], v[10:11], 0, s[6:7]
	global_store_dword v[10:11], v66, off
	v_fmac_f32_e32 v67, v66, v131
	v_lshl_add_u64 v[10:11], v[10:11], 0, s[6:7]
	global_store_dword v[10:11], v67, off
	v_fmac_f32_e32 v68, v67, v132
	v_lshl_add_u64 v[10:11], v[10:11], 0, s[6:7]
	global_store_dword v[10:11], v68, off
	v_fmac_f32_e32 v69, v68, v133
	v_lshl_add_u64 v[10:11], v[10:11], 0, s[6:7]
	global_store_dword v[10:11], v69, off
	v_fmac_f32_e32 v70, v69, v134
	v_lshl_add_u64 v[10:11], v[10:11], 0, s[6:7]
	global_store_dword v[10:11], v70, off
	v_fmac_f32_e32 v71, v70, v135
	v_lshl_add_u64 v[10:11], v[10:11], 0, s[6:7]
	global_store_dword v[10:11], v71, off
	v_fmac_f32_e32 v72, v71, v136
	v_lshl_add_u64 v[10:11], v[10:11], 0, s[6:7]
	global_store_dword v[10:11], v72, off
	v_fmac_f32_e32 v73, v72, v137
	v_lshl_add_u64 v[10:11], v[10:11], 0, s[6:7]
	global_store_dword v[10:11], v73, off
	v_fmac_f32_e32 v74, v73, v138
	v_lshl_add_u64 v[10:11], v[10:11], 0, s[6:7]
	global_store_dword v[10:11], v74, off
	v_fmac_f32_e32 v75, v74, v139
	v_lshl_add_u64 v[10:11], v[10:11], 0, s[6:7]
	global_store_dword v[10:11], v75, off
	v_fmac_f32_e32 v76, v75, v140
	v_lshl_add_u64 v[10:11], v[10:11], 0, s[6:7]
	global_store_dword v[10:11], v76, off
	v_fmac_f32_e32 v77, v76, v141
	v_lshl_add_u64 v[10:11], v[10:11], 0, s[6:7]
	global_store_dword v[10:11], v77, off
	v_fmac_f32_e32 v78, v77, v142
	v_lshl_add_u64 v[10:11], v[10:11], 0, s[6:7]
	global_store_dword v[10:11], v78, off
	v_fmac_f32_e32 v79, v78, v143
	v_lshl_add_u64 v[10:11], v[10:11], 0, s[6:7]
	global_store_dword v[10:11], v79, off
	v_fmac_f32_e32 v80, v79, v144
	v_lshl_add_u64 v[10:11], v[10:11], 0, s[6:7]
	global_store_dword v[10:11], v80, off
	v_fmac_f32_e32 v81, v80, v145
	v_lshl_add_u64 v[10:11], v[10:11], 0, s[6:7]
	global_store_dword v[10:11], v81, off
	v_fmac_f32_e32 v82, v81, v146
	v_lshl_add_u64 v[10:11], v[10:11], 0, s[6:7]
	global_store_dword v[10:11], v82, off
	v_fmac_f32_e32 v83, v82, v147
	v_lshl_add_u64 v[10:11], v[10:11], 0, s[6:7]
	global_store_dword v[10:11], v83, off
	v_fmac_f32_e32 v84, v83, v148
	v_lshl_add_u64 v[10:11], v[10:11], 0, s[6:7]
	global_store_dword v[10:11], v84, off
	v_fmac_f32_e32 v85, v84, v149
	v_lshl_add_u64 v[10:11], v[10:11], 0, s[6:7]
	global_store_dword v[10:11], v85, off
	v_fmac_f32_e32 v86, v85, v150
	v_lshl_add_u64 v[10:11], v[10:11], 0, s[6:7]
	global_store_dword v[10:11], v86, off
	v_fmac_f32_e32 v87, v86, v151
	v_lshl_add_u64 v[10:11], v[10:11], 0, s[6:7]
	global_store_dword v[10:11], v87, off
	v_fmac_f32_e32 v88, v87, v152
	v_lshl_add_u64 v[10:11], v[10:11], 0, s[6:7]
	global_store_dword v[10:11], v88, off
	v_fmac_f32_e32 v89, v88, v153
	v_lshl_add_u64 v[10:11], v[10:11], 0, s[6:7]
	global_store_dword v[10:11], v89, off
	v_fmac_f32_e32 v90, v89, v154
	v_lshl_add_u64 v[10:11], v[10:11], 0, s[6:7]
	global_store_dword v[10:11], v90, off
	v_fmac_f32_e32 v91, v90, v155
	s_waitcnt vmcnt(32)
; __device__ __forceinline__ int opaque_tid() { int t = threadIdx.x; asm volatile("" : "+v"(t)); return t; }
; DI void hgrn_h2(const Params& p, int item) {
;   const int bh = item >> 4, idx = (item & 15) * 256 + (opaque_tid() & 255), d = idx >> 6;
;   float S = 0.f;
;   float* ub = p.U + (size_t)bh * 64 * 4096 + idx;
;   const float* gb = p.G + (size_t)bh * 64 * 64 + d;
; #pragma unroll 8
;   for (int c = 0; c < 64; ++c) { const float u = ub[(size_t)c * 4096]; const float g = gb[c * 64]; ub[(size_t)c * 4096] = S; S = g * S + u; }
; }
	v_lshl_add_u64 v[10:11], v[10:11], 0, s[6:7]
	global_store_dword v[10:11], v91, off
	v_fmac_f32_e32 v92, v91, v156
	v_lshl_add_u64 v[10:11], v[10:11], 0, s[6:7]
	global_store_dword v[10:11], v92, off
	v_fmac_f32_e32 v93, v92, v157
	v_lshl_add_u64 v[10:11], v[10:11], 0, s[6:7]
	global_store_dword v[10:11], v93, off
	v_fmac_f32_e32 v94, v93, v158
	v_lshl_add_u64 v[10:11], v[10:11], 0, s[6:7]
	global_store_dword v[10:11], v94, off
	v_fmac_f32_e32 v95, v94, v159
	v_lshl_add_u64 v[10:11], v[10:11], 0, s[6:7]
	global_store_dword v[10:11], v95, off
	v_fmac_f32_e32 v96, v95, v160
	v_lshl_add_u64 v[10:11], v[10:11], 0, s[6:7]
	global_store_dword v[10:11], v96, off
	v_fmac_f32_e32 v97, v96, v161
	v_lshl_add_u64 v[10:11], v[10:11], 0, s[6:7]
	global_store_dword v[10:11], v97, off
	v_fmac_f32_e32 v98, v97, v162
	v_lshl_add_u64 v[10:11], v[10:11], 0, s[6:7]
	global_store_dword v[10:11], v98, off
	v_fmac_f32_e32 v99, v98, v163
	v_lshl_add_u64 v[10:11], v[10:11], 0, s[6:7]
	global_store_dword v[10:11], v99, off
	v_fmac_f32_e32 v100, v99, v164
	v_lshl_add_u64 v[10:11], v[10:11], 0, s[6:7]
	global_store_dword v[10:11], v100, off
	v_fmac_f32_e32 v101, v100, v165
	v_lshl_add_u64 v[10:11], v[10:11], 0, s[6:7]
	global_store_dword v[10:11], v101, off
	v_fmac_f32_e32 v102, v101, v166
	v_lshl_add_u64 v[10:11], v[10:11], 0, s[6:7]
	global_store_dword v[10:11], v102, off
	v_fmac_f32_e32 v103, v102, v167
	v_lshl_add_u64 v[10:11], v[10:11], 0, s[6:7]
	global_store_dword v[10:11], v103, off
	v_fmac_f32_e32 v104, v103, v168
	v_lshl_add_u64 v[10:11], v[10:11], 0, s[6:7]
	global_store_dword v[10:11], v104, off
	v_fmac_f32_e32 v105, v104, v169
	v_lshl_add_u64 v[10:11], v[10:11], 0, s[6:7]
	global_store_dword v[10:11], v105, off
	v_fmac_f32_e32 v106, v105, v170
	v_lshl_add_u64 v[10:11], v[10:11], 0, s[6:7]
	global_store_dword v[10:11], v106, off
	v_fmac_f32_e32 v107, v106, v171
	v_lshl_add_u64 v[10:11], v[10:11], 0, s[6:7]
	global_store_dword v[10:11], v107, off
	v_fmac_f32_e32 v108, v107, v172
	v_lshl_add_u64 v[10:11], v[10:11], 0, s[6:7]
	global_store_dword v[10:11], v108, off
	v_fmac_f32_e32 v109, v108, v173
	v_lshl_add_u64 v[10:11], v[10:11], 0, s[6:7]
	global_store_dword v[10:11], v109, off
	v_fmac_f32_e32 v110, v109, v174
	v_lshl_add_u64 v[10:11], v[10:11], 0, s[6:7]
	global_store_dword v[10:11], v110, off
	v_fmac_f32_e32 v111, v110, v175
	v_lshl_add_u64 v[10:11], v[10:11], 0, s[6:7]
	global_store_dword v[10:11], v111, off
	v_fmac_f32_e32 v112, v111, v176
	v_lshl_add_u64 v[10:11], v[10:11], 0, s[6:7]
	global_store_dword v[10:11], v112, off
	v_fmac_f32_e32 v113, v112, v177
	v_lshl_add_u64 v[10:11], v[10:11], 0, s[6:7]
	global_store_dword v[10:11], v113, off
	v_fmac_f32_e32 v114, v113, v178
	v_lshl_add_u64 v[10:11], v[10:11], 0, s[6:7]
	global_store_dword v[10:11], v114, off
	v_fmac_f32_e32 v115, v114, v179
	v_lshl_add_u64 v[10:11], v[10:11], 0, s[6:7]
	global_store_dword v[10:11], v115, off
	v_fmac_f32_e32 v116, v115, v180
	v_lshl_add_u64 v[10:11], v[10:11], 0, s[6:7]
	global_store_dword v[10:11], v116, off
	v_fmac_f32_e32 v117, v116, v181
	v_lshl_add_u64 v[10:11], v[10:11], 0, s[6:7]
	global_store_dword v[10:11], v117, off
	v_fmac_f32_e32 v118, v117, v182
	v_lshl_add_u64 v[10:11], v[10:11], 0, s[6:7]
	global_store_dword v[10:11], v118, off
	v_fmac_f32_e32 v119, v118, v183
	v_lshl_add_u64 v[10:11], v[10:11], 0, s[6:7]
	global_store_dword v[10:11], v119, off
	v_fmac_f32_e32 v120, v119, v184
	v_lshl_add_u64 v[10:11], v[10:11], 0, s[6:7]
	global_store_dword v[10:11], v120, off
	v_fmac_f32_e32 v121, v120, v185
	v_lshl_add_u64 v[10:11], v[10:11], 0, s[6:7]
	global_store_dword v[10:11], v121, off
	v_fmac_f32_e32 v122, v121, v186
	v_lshl_add_u64 v[10:11], v[10:11], 0, s[6:7]
	global_store_dword v[10:11], v122, off
	v_fmac_f32_e32 v123, v122, v187
	s_branch .LBB0_653
